# latent diff-attention loop: MFMA->VALU pad 25->12 states, inline-asm pads between v_max3 links removed, staged vmcnt waits merged
# speedup vs baseline: 1.0113x; 1.0072x over previous
; template <int KW, int DV, bool NA> ...
;     ...
;     auto prefetch = [&](int i, u32x4 (&kreg)[NK], u32x4 (&vreg)[NV]) {
;         const size_t rb = rowbase(i);
; #pragma unroll
;         for (int e = 0; e < NK; ++e) { const int c = tid + 512 * e; kreg[e] = *(const u32x4*)(Kg + (rb + c / KCH) * pitch + (c % KCH) * 8); }
; #pragma unroll
;         for (int e = 0; e < NV; ++e) { const int c = tid + 512 * e; vreg[e] = *(const u32x4*)(Vg + (rb + c / VCH) * pitch + (c % VCH) * 8); }
;     };
;     auto stash = [&](int st, const u32x4 (&kreg)[NK], const u32x4 (&vreg)[NV]) {
;         unsigned char* Kt = lds + st * STAGE; unsigned char* Vt = Kt + 64 * KSTR;
; #pragma unroll
;         for (int e = 0; e < NK; ++e) { const int c = tid + 512 * e; *(u32x4*)(Kt + (c / KCH) * KSTR + (c % KCH) * 16) = kreg[e]; }
; #pragma unroll
;         for (int e = 0; e < NV; ++e) { const int c = tid + 512 * e; *(u32x4*)(Vt + (c / VCH) * VSTR + (c % VCH) * 16) = vreg[e]; }
;     };
;     float m_ref = 0.f, l_run = 0.f; bool first = true;
;     u32x4 pw[4];
;     f32x16 negm = {}; asm volatile("" : "+v"(negm));
; #pragma unroll
;     for (int d = 0; d < DV / 32; ++d) o[d] = (f32x16){};
;     auto is_active = [&](int i) -> bool { return (i >= n1) || (i >= act_lo && i < act_hi); };
;     auto tile = [&](int i, const unsigned char* Kt, const unsigned char* Vt) {
;         constexpr int DT = DV / 32;
;         f32x16 p0, p1;
; #pragma unroll
;         for (int d0 = 0; d0 < 4; ++d0) {
;             const bf16x8 a0 = *(const bf16x8*)(Kt + q32 * KSTR + (kcoff + 16 * d0 + 8 * hi) * 2);
;             const bf16x8 a1 = *(const bf16x8*)(Kt + (32 + q32) * KSTR + (kcoff + 16 * d0 + 8 * hi) * 2);
;             if (d0 == 0) { p0 = __builtin_amdgcn_mfma_f32_32x32x16_bf16(a0, qf[0], negm, 0, 0, 0); p1 = __builtin_amdgcn_mfma_f32_32x32x16_bf16(a1, qf[0], negm, 0, 0, 0); }
;             else { p0 = __builtin_amdgcn_mfma_f32_32x32x16_bf16(a0, qf[d0], p0, 0, 0, 0); p1 = __builtin_amdgcn_mfma_f32_32x32x16_bf16(a1, qf[d0], p1, 0, 0, 0); }
;         }
;         if (NA && i < n1) {
;             const int kr = na_row0 + i, dr = kr - na_r + 7;
;             const int cs = min(max(na_c - 8, 0), 48);
;             const float* rb = rpbs + dr * 31 - na_c + 15;
; #pragma unroll
;             for (int r = 0; r < 16; ++r) {
;                 const int kc0 = (r & 3) + 8 * (r >> 2) + 4 * hi, kc1 = kc0 + 32;
.LBB0_591:
	s_mov_b32 s11, s2
	s_mul_i32 s2, s10, 0x9400
	s_add_i32 s13, s2, 0
	v_add3_u32 v82, s13, v187, v188
	s_waitcnt vmcnt(0)
	ds_write_b128 v82, v[130:133]
	v_add3_u32 v82, s13, v189, v190
	s_add_i32 s12, s8, -4
	ds_write_b128 v82, v[134:137]
	v_add3_u32 v82, s13, v191, v188
	ds_write_b128 v82, v[138:141] offset:17408
	v_add3_u32 v82, s13, v192, v190
	s_cmp_gt_u32 s12, 64
	ds_write_b128 v82, v[142:145] offset:17408
	s_cbranch_scc1 .LBB0_593
	s_cmp_lt_u32 s12, 61
	s_cselect_b64 vcc, -1, 0
	s_and_b64 s[4:5], vcc, exec
	s_cselect_b32 s2, 0, 0xffffffc0
	s_add_i32 s2, s2, s8
	s_add_i32 s2, s2, -1
	v_cndmask_b32_e32 v83, v173, v167, vcc
	v_cndmask_b32_e32 v82, v172, v166, vcc
	s_lshl_b64 s[4:5], s[2:3], 6
	v_lshl_add_u64 v[82:83], s[4:5], 0, v[82:83]
	v_lshl_add_u64 v[84:85], v[82:83], 0, v[168:169]
	v_mad_u64_u32 v[86:87], s[4:5], v84, s33, v[174:175]
	v_lshl_add_u64 v[82:83], v[82:83], 0, v[170:171]
	v_mad_i32_i24 v87, v85, s33, v87
	v_mad_u64_u32 v[88:89], s[4:5], v82, s33, v[176:177]
	v_mad_i32_i24 v89, v83, s33, v89
	global_load_dwordx4 v[130:133], v[86:87], off
	global_load_dwordx4 v[134:137], v[88:89], off
	v_mad_u64_u32 v[86:87], s[4:5], v84, s33, v[178:179]
	v_mad_i32_i24 v87, v85, s33, v87
	v_mad_u64_u32 v[84:85], s[4:5], v82, s33, v[180:181]
	v_mad_i32_i24 v85, v83, s33, v85
	global_load_dwordx4 v[138:141], v[86:87], off
	global_load_dwordx4 v[142:145], v[84:85], off
.LBB0_593:
	s_mul_i32 s2, s9, 0x9400
	s_add_i32 s2, s2, 0
	v_add3_u32 v204, s2, v193, v194
	ds_read_b128 v[82:85], v204
	ds_read_b128 v[198:201], v204 offset:8704
	s_xor_b64 s[4:5], s[0:1], -1
	s_and_b64 vcc, exec, s[4:5]
	s_waitcnt lgkmcnt(1)
	v_mfma_f32_32x32x16_bf16 v[98:113], v[82:85], v[114:117], v[66:81]
	s_waitcnt lgkmcnt(0)
	v_mfma_f32_32x32x16_bf16 v[82:97], v[198:201], v[114:117], v[66:81]
	ds_read_b128 v[198:201], v204 offset:32
	s_waitcnt lgkmcnt(0)
	v_mfma_f32_32x32x16_bf16 v[98:113], v[198:201], v[118:121], v[98:113]
	ds_read_b128 v[198:201], v204 offset:8736
	s_waitcnt lgkmcnt(0)
	v_mfma_f32_32x32x16_bf16 v[82:97], v[198:201], v[118:121], v[82:97]
	ds_read_b128 v[198:201], v204 offset:64
	s_waitcnt lgkmcnt(0)
	v_mfma_f32_32x32x16_bf16 v[98:113], v[198:201], v[122:125], v[98:113]
	ds_read_b128 v[198:201], v204 offset:8768
	s_waitcnt lgkmcnt(0)
	v_mfma_f32_32x32x16_bf16 v[82:97], v[198:201], v[122:125], v[82:97]
	ds_read_b128 v[198:201], v204 offset:96
	s_waitcnt lgkmcnt(0)
	v_mfma_f32_32x32x16_bf16 v[98:113], v[198:201], v[126:129], v[98:113]
	ds_read_b128 v[198:201], v204 offset:8800
	s_waitcnt lgkmcnt(0)
	v_mfma_f32_32x32x16_bf16 v[82:97], v[198:201], v[126:129], v[82:97]
	s_nop 10
	s_nop 0
	v_max3_f32 v198, v98, v99, v82
	v_max3_f32 v199, v100, v101, v83
	v_max3_f32 v198, v198, v84, v85
	v_max3_f32 v199, v199, v104, v105
	v_max3_f32 v198, v198, v102, v103
	v_max3_f32 v199, v199, v88, v89
	v_max3_f32 v198, v198, v86, v87
	v_max3_f32 v199, v199, v108, v109
	v_max3_f32 v198, v198, v106, v107
	v_max3_f32 v199, v199, v92, v93
	v_max3_f32 v198, v198, v90, v91
	v_max3_f32 v199, v199, v112, v113
	v_max3_f32 v198, v198, v110, v111
	v_max3_f32 v199, v199, v96, v97
	v_max3_f32 v198, v198, v94, v95
	v_max3_f32 v198, v198, v199, v199
	v_mov_b32_e32 v199, v198
	s_nop 1
	v_permlane32_swap_b32_e32 v198, v199
	v_max_f32_e32 v199, v199, v199
	v_max_f32_e32 v198, v198, v198
	v_max_f32_e32 v198, v198, v199
	s_cbranch_vccz .LBB0_595
	v_cmp_lt_f32_e32 vcc, s80, v198
	s_cmp_lg_u64 vcc, 0
	s_cselect_b64 s[4:5], -1, 0
	s_cbranch_execz .LBB0_596
	s_branch .LBB0_597

; template <int KW, int DV, bool NA> ...
;     ...
;     auto prefetch = [&](int i, u32x4 (&kreg)[NK], u32x4 (&vreg)[NV]) {
;         const size_t rb = rowbase(i);
; #pragma unroll
;         for (int e = 0; e < NK; ++e) { const int c = tid + 512 * e; kreg[e] = *(const u32x4*)(Kg + (rb + c / KCH) * pitch + (c % KCH) * 8); }
; #pragma unroll
;         for (int e = 0; e < NV; ++e) { const int c = tid + 512 * e; vreg[e] = *(const u32x4*)(Vg + (rb + c / VCH) * pitch + (c % VCH) * 8); }
;     };
;     ...
;         const unsigned vb = (unsigned)(uintptr_t)(Vt + (4 * hi + ((lane & 15) >> 2)) * VSTR + (16 * ((lane >> 4) & 1) + 4 * (lane & 3)) * 2);
;         s16x4 lo[DT], hh[DT];
;     ...
; #pragma unroll
;         for (int d = 0; d < DT; ++d) TR_ISSUE(0, d);
;         float ps = 0.f;
;         SM_SLICE(p0, 0, 8); pw[0] = PACK8(p0, 0);
; #pragma unroll
;         for (int d = 0; d < DT; ++d) {
;             LGKM_WAIT(2 * (DT - 1));
;             o[d] = __builtin_amdgcn_mfma_f32_32x32x16_bf16(PV_VF(d), __builtin_bit_cast(bf16x8, pw[0]), o[d], 0, 0, 0);
;             TR_ISSUE(1, d);
;             SM_SLICE(p0, 8 + d * (8 / DT), 8 + (d + 1) * (8 / DT));
;             __builtin_amdgcn_sched_barrier(0);
;         }
;         pw[1] = PACK8(p0, 8);
; #pragma unroll
;         for (int d = 0; d < DT; ++d) {
;             LGKM_WAIT(2 * (DT - 1));
;             o[d] = __builtin_amdgcn_mfma_f32_32x32x16_bf16(PV_VF(d), __builtin_bit_cast(bf16x8, pw[1]), o[d], 0, 0, 0);
;             TR_ISSUE(2, d);
;             SM_SLICE(p1, d * (8 / DT), (d + 1) * (8 / DT));
;             __builtin_amdgcn_sched_barrier(0);
;         }
;         pw[2] = PACK8(p1, 0);
; #pragma unroll
;         for (int d = 0; d < DT; ++d) {
;             LGKM_WAIT(2 * (DT - 1));
;             o[d] = __builtin_amdgcn_mfma_f32_32x32x16_bf16(PV_VF(d), __builtin_bit_cast(bf16x8, pw[2]), o[d], 0, 0, 0);
;             TR_ISSUE(3, d);
;             SM_SLICE(p1, 8 + d * (8 / DT), 8 + (d + 1) * (8 / DT));
;             __builtin_amdgcn_sched_barrier(0);
;         }
;         pw[3] = PACK8(p1, 8);
;         l_run += ps;
;         asm volatile("s_waitcnt lgkmcnt(0)" ::: "memory"); __builtin_amdgcn_sched_barrier(0);
; #pragma unroll
;         for (int d = 0; d < DT; ++d) o[d] = __builtin_amdgcn_mfma_f32_32x32x16_bf16(PV_VF(d), __builtin_bit_cast(bf16x8, pw[3]), o[d], 0, 0, 0);
.LBB0_599:
	v_add_u32_e32 v198, s2, v195
	v_add3_u32 v204, v198, v0, s90
	ds_read_b64_tr_b16 v[198:199], v204 offset:0
	ds_read_b64_tr_b16 v[200:201], v204 offset:2560
	ds_read_b64_tr_b16 v[206:207], v204 offset:64
	ds_read_b64_tr_b16 v[208:209], v204 offset:2624
	ds_read_b64_tr_b16 v[210:211], v204 offset:128
	ds_read_b64_tr_b16 v[212:213], v204 offset:2688
	ds_read_b64_tr_b16 v[214:215], v204 offset:192
	ds_read_b64_tr_b16 v[216:217], v204 offset:2752
	v_exp_f32_e32 v98, v98
	v_exp_f32_e32 v99, v99
	v_exp_f32_e32 v100, v100
	v_exp_f32_e32 v101, v101
	v_exp_f32_e32 v102, v102
	v_exp_f32_e32 v103, v103
	v_exp_f32_e32 v104, v104
	v_exp_f32_e32 v105, v105
	s_waitcnt lgkmcnt(6)
	v_cvt_pk_bf16_f32 v218, v98, v99
	v_cvt_pk_bf16_f32 v219, v100, v101
	v_cvt_pk_bf16_f32 v220, v102, v103
	v_cvt_pk_bf16_f32 v221, v104, v105
	s_nop 1
	v_mfma_f32_32x32x16_bf16 v[50:65], v[198:201], v[218:221], v[50:65]
	ds_read_b64_tr_b16 v[198:199], v204 offset:5120
	v_exp_f32_e32 v106, v106
	v_exp_f32_e32 v107, v107
	ds_read_b64_tr_b16 v[200:201], v204 offset:7680
	s_waitcnt lgkmcnt(6)
	v_mfma_f32_32x32x16_bf16 v[34:49], v[206:209], v[218:221], v[34:49]
	ds_read_b64_tr_b16 v[206:207], v204 offset:5184
	v_exp_f32_e32 v108, v108
	v_exp_f32_e32 v109, v109
	ds_read_b64_tr_b16 v[208:209], v204 offset:7744
	s_waitcnt lgkmcnt(6)
	v_mfma_f32_32x32x16_bf16 v[18:33], v[210:213], v[218:221], v[18:33]
	ds_read_b64_tr_b16 v[210:211], v204 offset:5248
	v_exp_f32_e32 v110, v110
	v_exp_f32_e32 v111, v111
	ds_read_b64_tr_b16 v[212:213], v204 offset:7808
	s_waitcnt lgkmcnt(6)
	v_mfma_f32_32x32x16_bf16 v[2:17], v[214:217], v[218:221], v[2:17]
	ds_read_b64_tr_b16 v[214:215], v204 offset:5312
	v_exp_f32_e32 v112, v112
	v_exp_f32_e32 v113, v113
	ds_read_b64_tr_b16 v[216:217], v204 offset:7872
	s_waitcnt lgkmcnt(6)
	v_cvt_pk_bf16_f32 v218, v106, v107
	v_cvt_pk_bf16_f32 v219, v108, v109
	v_cvt_pk_bf16_f32 v220, v110, v111
	v_cvt_pk_bf16_f32 v221, v112, v113
	s_nop 1
	v_mfma_f32_32x32x16_bf16 v[50:65], v[198:201], v[218:221], v[50:65]
	ds_read_b64_tr_b16 v[198:199], v204 offset:10240
	v_exp_f32_e32 v82, v82
	v_exp_f32_e32 v83, v83
	ds_read_b64_tr_b16 v[200:201], v204 offset:12800
	s_waitcnt lgkmcnt(6)
	v_mfma_f32_32x32x16_bf16 v[34:49], v[206:209], v[218:221], v[34:49]
	ds_read_b64_tr_b16 v[206:207], v204 offset:10304
	v_exp_f32_e32 v84, v84
	v_exp_f32_e32 v85, v85
	ds_read_b64_tr_b16 v[208:209], v204 offset:12864
	s_waitcnt lgkmcnt(6)
	v_mfma_f32_32x32x16_bf16 v[18:33], v[210:213], v[218:221], v[18:33]
	ds_read_b64_tr_b16 v[210:211], v204 offset:10368
	v_exp_f32_e32 v86, v86
	v_exp_f32_e32 v87, v87
	ds_read_b64_tr_b16 v[212:213], v204 offset:12928
	s_waitcnt lgkmcnt(6)
	v_mfma_f32_32x32x16_bf16 v[2:17], v[214:217], v[218:221], v[2:17]
	ds_read_b64_tr_b16 v[214:215], v204 offset:10432
	v_exp_f32_e32 v88, v88
	v_exp_f32_e32 v89, v89
	ds_read_b64_tr_b16 v[216:217], v204 offset:12992
	s_waitcnt lgkmcnt(6)
	v_cvt_pk_bf16_f32 v218, v82, v83
	v_cvt_pk_bf16_f32 v219, v84, v85
	v_cvt_pk_bf16_f32 v220, v86, v87
	v_cvt_pk_bf16_f32 v221, v88, v89
	s_nop 1
	v_mfma_f32_32x32x16_bf16 v[50:65], v[198:201], v[218:221], v[50:65]
	ds_read_b64_tr_b16 v[198:199], v204 offset:15360
	ds_read_b64_tr_b16 v[200:201], v204 offset:17920
	s_waitcnt lgkmcnt(6)
	v_mfma_f32_32x32x16_bf16 v[34:49], v[206:209], v[218:221], v[34:49]
	ds_read_b64_tr_b16 v[206:207], v204 offset:15424
	ds_read_b64_tr_b16 v[208:209], v204 offset:17984
	s_waitcnt lgkmcnt(6)
	v_mfma_f32_32x32x16_bf16 v[18:33], v[210:213], v[218:221], v[18:33]
	ds_read_b64_tr_b16 v[210:211], v204 offset:15488
	ds_read_b64_tr_b16 v[212:213], v204 offset:18048
	s_waitcnt lgkmcnt(6)
	v_mfma_f32_32x32x16_bf16 v[2:17], v[214:217], v[218:221], v[2:17]
	ds_read_b64_tr_b16 v[214:215], v204 offset:15552
	v_exp_f32_e32 v90, v90
	v_exp_f32_e32 v91, v91
	v_exp_f32_e32 v92, v92
	v_exp_f32_e32 v93, v93
	v_exp_f32_e32 v94, v94
	v_exp_f32_e32 v95, v95
	v_exp_f32_e32 v96, v96
	v_exp_f32_e32 v97, v97
	ds_read_b64_tr_b16 v[216:217], v204 offset:18112
	s_waitcnt lgkmcnt(0)
	v_cvt_pk_bf16_f32 v218, v90, v91
	v_cvt_pk_bf16_f32 v219, v92, v93
	v_cvt_pk_bf16_f32 v220, v94, v95
	v_cvt_pk_bf16_f32 v221, v96, v97
	s_nop 1
	v_mfma_f32_32x32x16_bf16 v[50:65], v[198:201], v[218:221], v[50:65]
	s_cmpk_gt_u32 s12, 0x41
	s_barrier
	v_mfma_f32_32x32x16_bf16 v[34:49], v[206:209], v[218:221], v[34:49]
	v_mfma_f32_32x32x16_bf16 v[18:33], v[210:213], v[218:221], v[18:33]
	v_mfma_f32_32x32x16_bf16 v[2:17], v[214:217], v[218:221], v[2:17]
	s_cbranch_scc1 .LBB0_602
	s_mul_i32 s0, s11, 0x9400
	s_add_i32 s0, s0, 0
	v_add3_u32 v198, s0, v187, v188
	s_waitcnt vmcnt(0)
	ds_write_b128 v198, v[146:149]
	v_add3_u32 v198, s0, v189, v190
	ds_write_b128 v198, v[150:153]
	v_add3_u32 v198, s0, v191, v188
	ds_write_b128 v198, v[154:157] offset:17408
	v_add3_u32 v198, s0, v192, v190
	s_cmp_gt_u32 s12, 63
	ds_write_b128 v198, v[158:161] offset:17408
	s_cbranch_scc1 .LBB0_602
	s_cmp_lt_u32 s12, 60
	s_cselect_b64 vcc, -1, 0
	s_and_b64 s[0:1], vcc, exec
	s_cselect_b32 s0, 0, 0xffffffc0
	s_add_i32 s2, s0, s8
	v_cndmask_b32_e32 v147, v173, v167, vcc
	v_cndmask_b32_e32 v146, v172, v166, vcc
	s_lshl_b64 s[0:1], s[2:3], 6
	v_lshl_add_u64 v[146:147], s[0:1], 0, v[146:147]
	v_lshl_add_u64 v[154:155], v[146:147], 0, v[168:169]
	v_lshl_add_u64 v[156:157], v[146:147], 0, v[170:171]
	v_mad_u64_u32 v[148:149], s[0:1], v154, s33, v[174:175]
	v_mad_u64_u32 v[150:151], s[0:1], v156, s33, v[176:177]
	v_mad_u64_u32 v[158:159], s[0:1], v154, s33, v[178:179]
	v_mad_u64_u32 v[160:161], s[0:1], v156, s33, v[180:181]
	v_mad_i32_i24 v149, v155, s33, v149
	v_mad_i32_i24 v151, v157, s33, v151
	v_mad_i32_i24 v159, v155, s33, v159
	v_mad_i32_i24 v161, v157, s33, v161
	global_load_dwordx4 v[146:149], v[148:149], off
	s_nop 0
	global_load_dwordx4 v[150:153], v[150:151], off
	s_nop 0
	global_load_dwordx4 v[154:157], v[158:159], off
	s_nop 0
	global_load_dwordx4 v[158:161], v[160:161], off
; template <int KW, int DV, bool NA> ...
;     ...
;             const bf16x8 a0 = *(const bf16x8*)(Kt + q32 * KSTR + (kcoff + 16 * d0 + 8 * hi) * 2);
;             const bf16x8 a1 = *(const bf16x8*)(Kt + (32 + q32) * KSTR + (kcoff + 16 * d0 + 8 * hi) * 2);
;             if (d0 == 0) { p0 = __builtin_amdgcn_mfma_f32_32x32x16_bf16(a0, qf[0], negm, 0, 0, 0); p1 = __builtin_amdgcn_mfma_f32_32x32x16_bf16(a1, qf[0], negm, 0, 0, 0); }
;             else { p0 = __builtin_amdgcn_mfma_f32_32x32x16_bf16(a0, qf[d0], p0, 0, 0, 0); p1 = __builtin_amdgcn_mfma_f32_32x32x16_bf16(a1, qf[d0], p1, 0, 0, 0); }
;         }
;         if (NA && i < n1) {
;             const int kr = na_row0 + i, dr = kr - na_r + 7;
;             const int cs = min(max(na_c - 8, 0), 48);
;             const float* rb = rpbs + dr * 31 - na_c + 15;
; #pragma unroll
;             for (int r = 0; r < 16; ++r) {
;                 const int kc0 = (r & 3) + 8 * (r >> 2) + 4 * hi, kc1 = kc0 + 32;
;                 const bool ok0 = (kc0 >= cs) && (kc0 < cs + 16), ok1 = (kc1 >= cs) && (kc1 < cs + 16);
;                 p0[r] = ok0 ? p0[r] + rb[kc0] : -1e30f;
;                 p1[r] = ok1 ? p1[r] + rb[kc1] : -1e30f;
;             }
;         }
;         asm volatile("s_nop 15\n\ts_nop 7" : "+v"(p0), "+v"(p1));
;         float mxa = max3f_(p0[0], p0[1], p1[0]), mxb = max3f_(p0[2], p0[3], p1[1]);
;         mxa = max3f_(mxa, p1[2], p1[3]);
; #pragma unroll
;         for (int r = 4; r < 16; r += 4) { mxa = max3f_(mxa, p0[r], p0[r + 1]); mxb = max3f_(mxb, p0[r + 2], p0[r + 3]); mxa = max3f_(mxa, p1[r], p1[r + 1]); mxb = max3f_(mxb, p1[r + 2], p1[r + 3]); }
;         float mx = max3f_(mxa, mxb, mxb);
;         mx = xor32_max(mx);
;         if (first || __any(mx > 6.f)) {
;             const float dl = first ? mx : fmaxf(mx, 0.f);
;             const float f = first ? 0.f : __builtin_amdgcn_exp2f(-dl);
;             m_ref += dl; l_run *= f;
; #pragma unroll
;             for (int r = 0; r < 16; ++r) negm[r] = -m_ref;
;             asm volatile("" : "+v"(negm));
; #pragma unroll
;             for (int r = 0; r < 16; ++r) { p0[r] -= dl; p1[r] -= dl; }
; #pragma unroll
;             for (int d = 0; d < DT; ++d)
; #pragma unroll
;                 for (int r = 0; r < 16; ++r) o[d][r] *= f;
;     ...
;         l_run += ps;
.LBB0_602:
	v_add_f32_e32 v98, 0, v98
	v_add_f32_e32 v98, v99, v98
	v_add_f32_e32 v98, v100, v98
	v_add_f32_e32 v98, v101, v98
	v_add_f32_e32 v98, v102, v98
	v_add_f32_e32 v98, v103, v98
	v_add_f32_e32 v98, v104, v98
	v_add_f32_e32 v98, v105, v98
	v_add_f32_e32 v98, v106, v98
	v_add_f32_e32 v98, v107, v98
	v_add_f32_e32 v98, v108, v98
	v_add_f32_e32 v98, v109, v98
	v_add_f32_e32 v98, v110, v98
	v_add_f32_e32 v98, v111, v98
	v_add_f32_e32 v98, v112, v98
	v_add_f32_e32 v98, v113, v98
	v_add_f32_e32 v82, v82, v98
	v_add_f32_e32 v82, v83, v82
	v_add_f32_e32 v82, v84, v82
	v_add_f32_e32 v82, v85, v82
	v_add_f32_e32 v82, v86, v82
	v_add_f32_e32 v82, v87, v82
	v_add_f32_e32 v82, v88, v82
	v_add_f32_e32 v82, v89, v82
	v_add_f32_e32 v82, v90, v82
	v_add_f32_e32 v82, v91, v82
	v_add_f32_e32 v82, v92, v82
	v_add_f32_e32 v82, v93, v82
	v_add_f32_e32 v82, v94, v82
	v_add_f32_e32 v82, v95, v82
	v_add_f32_e32 v82, v96, v82
	v_add_f32_e32 v82, v97, v82
	v_add3_u32 v204, s13, v193, v194
	v_add_f32_e32 v197, v197, v82
	ds_read_b128 v[198:201], v204 offset:8704
	ds_read_b128 v[82:85], v204
	ds_read_b128 v[206:209], v204 offset:32
	s_waitcnt lgkmcnt(1)
	v_mfma_f32_32x32x16_bf16 v[98:113], v[82:85], v[114:117], v[66:81]
	v_mfma_f32_32x32x16_bf16 v[82:97], v[198:201], v[114:117], v[66:81]
	ds_read_b128 v[198:201], v204 offset:8736
	s_waitcnt lgkmcnt(1)
	v_mfma_f32_32x32x16_bf16 v[98:113], v[206:209], v[118:121], v[98:113]
	s_waitcnt lgkmcnt(0)
	v_mfma_f32_32x32x16_bf16 v[82:97], v[198:201], v[118:121], v[82:97]
	ds_read_b128 v[198:201], v204 offset:8768
	ds_read_b128 v[206:209], v204 offset:64
	s_waitcnt lgkmcnt(0)
	v_mfma_f32_32x32x16_bf16 v[98:113], v[206:209], v[122:125], v[98:113]
	v_mfma_f32_32x32x16_bf16 v[82:97], v[198:201], v[122:125], v[82:97]
	ds_read_b128 v[198:201], v204 offset:8800
	ds_read_b128 v[206:209], v204 offset:96
	s_waitcnt lgkmcnt(0)
	v_mfma_f32_32x32x16_bf16 v[98:113], v[206:209], v[126:129], v[98:113]
	v_mfma_f32_32x32x16_bf16 v[82:97], v[198:201], v[126:129], v[82:97]
	s_nop 10
	s_nop 0
	v_max3_f32 v198, v98, v99, v82
	v_max3_f32 v199, v100, v101, v83
	v_max3_f32 v198, v198, v84, v85
	v_max3_f32 v199, v199, v104, v105
	v_max3_f32 v198, v198, v102, v103
	v_max3_f32 v199, v199, v88, v89
	v_max3_f32 v198, v198, v86, v87
	v_max3_f32 v199, v199, v108, v109
	v_max3_f32 v198, v198, v106, v107
	v_max3_f32 v199, v199, v92, v93
	v_max3_f32 v198, v198, v90, v91
	v_max3_f32 v199, v199, v112, v113
	v_max3_f32 v198, v198, v110, v111
	v_max3_f32 v199, v199, v96, v97
	v_max3_f32 v198, v198, v94, v95
	v_max3_f32 v198, v198, v199, v199
	v_mov_b32_e32 v199, v198
	s_nop 1
	v_permlane32_swap_b32_e32 v198, v199
	v_max_f32_e32 v199, v199, v199
	v_max_f32_e32 v198, v198, v198
	v_max_f32_e32 v198, v198, v199
	v_cmp_lt_f32_e32 vcc, s80, v198
	s_cbranch_vccz .LBB0_604
	v_max_f32_e32 v66, v198, v198
	v_max_f32_e32 v198, 0, v66
	v_exp_f32_e64 v200, -v198
	v_add_f32_e32 v196, v196, v198
	v_xor_b32_e32 v66, 0x80000000, v196
	v_mov_b32_e32 v67, v66
	v_mul_f32_e32 v197, v197, v200
	v_mov_b32_e32 v68, v66
	v_mov_b32_e32 v69, v66
	v_mov_b32_e32 v70, v66
	v_mov_b32_e32 v71, v66
	v_mov_b32_e32 v72, v66
	v_mov_b32_e32 v73, v66
	v_mov_b32_e32 v74, v66
	v_mov_b32_e32 v75, v66
	v_mov_b32_e32 v76, v66
	v_mov_b32_e32 v77, v66
	v_mov_b32_e32 v78, v66
	v_mov_b32_e32 v79, v66
	v_mov_b32_e32 v80, v66
	v_mov_b32_e32 v81, v66
	v_pk_add_f32 v[98:99], v[98:99], v[198:199] op_sel_hi:[1,0] neg_lo:[0,1] neg_hi:[0,1]
	v_pk_add_f32 v[82:83], v[82:83], v[198:199] op_sel_hi:[1,0] neg_lo:[0,1] neg_hi:[0,1]
	v_pk_add_f32 v[100:101], v[100:101], v[198:199] op_sel_hi:[1,0] neg_lo:[0,1] neg_hi:[0,1]
	v_pk_add_f32 v[84:85], v[84:85], v[198:199] op_sel_hi:[1,0] neg_lo:[0,1] neg_hi:[0,1]
	v_pk_add_f32 v[102:103], v[102:103], v[198:199] op_sel_hi:[1,0] neg_lo:[0,1] neg_hi:[0,1]
	v_pk_add_f32 v[86:87], v[86:87], v[198:199] op_sel_hi:[1,0] neg_lo:[0,1] neg_hi:[0,1]
	v_pk_add_f32 v[104:105], v[104:105], v[198:199] op_sel_hi:[1,0] neg_lo:[0,1] neg_hi:[0,1]
	v_pk_add_f32 v[88:89], v[88:89], v[198:199] op_sel_hi:[1,0] neg_lo:[0,1] neg_hi:[0,1]
	v_pk_add_f32 v[106:107], v[106:107], v[198:199] op_sel_hi:[1,0] neg_lo:[0,1] neg_hi:[0,1]
	v_pk_add_f32 v[90:91], v[90:91], v[198:199] op_sel_hi:[1,0] neg_lo:[0,1] neg_hi:[0,1]
	v_pk_add_f32 v[108:109], v[108:109], v[198:199] op_sel_hi:[1,0] neg_lo:[0,1] neg_hi:[0,1]
	v_pk_add_f32 v[92:93], v[92:93], v[198:199] op_sel_hi:[1,0] neg_lo:[0,1] neg_hi:[0,1]
	v_pk_add_f32 v[110:111], v[110:111], v[198:199] op_sel_hi:[1,0] neg_lo:[0,1] neg_hi:[0,1]
	v_pk_add_f32 v[94:95], v[94:95], v[198:199] op_sel_hi:[1,0] neg_lo:[0,1] neg_hi:[0,1]
	v_pk_add_f32 v[112:113], v[112:113], v[198:199] op_sel_hi:[1,0] neg_lo:[0,1] neg_hi:[0,1]
	v_pk_add_f32 v[96:97], v[96:97], v[198:199] op_sel_hi:[1,0] neg_lo:[0,1] neg_hi:[0,1]
	v_pk_mul_f32 v[64:65], v[64:65], v[200:201] op_sel_hi:[1,0]
	v_pk_mul_f32 v[62:63], v[62:63], v[200:201] op_sel_hi:[1,0]
	v_pk_mul_f32 v[60:61], v[60:61], v[200:201] op_sel_hi:[1,0]
	v_pk_mul_f32 v[58:59], v[58:59], v[200:201] op_sel_hi:[1,0]
	v_pk_mul_f32 v[56:57], v[56:57], v[200:201] op_sel_hi:[1,0]
	v_pk_mul_f32 v[54:55], v[54:55], v[200:201] op_sel_hi:[1,0]
	v_pk_mul_f32 v[52:53], v[52:53], v[200:201] op_sel_hi:[1,0]
	v_pk_mul_f32 v[50:51], v[50:51], v[200:201] op_sel_hi:[1,0]
	v_pk_mul_f32 v[48:49], v[48:49], v[200:201] op_sel_hi:[1,0]
	v_pk_mul_f32 v[46:47], v[46:47], v[200:201] op_sel_hi:[1,0]
	v_pk_mul_f32 v[44:45], v[44:45], v[200:201] op_sel_hi:[1,0]
	v_pk_mul_f32 v[42:43], v[42:43], v[200:201] op_sel_hi:[1,0]
	v_pk_mul_f32 v[40:41], v[40:41], v[200:201] op_sel_hi:[1,0]
	v_pk_mul_f32 v[38:39], v[38:39], v[200:201] op_sel_hi:[1,0]
	v_pk_mul_f32 v[36:37], v[36:37], v[200:201] op_sel_hi:[1,0]
	v_pk_mul_f32 v[34:35], v[34:35], v[200:201] op_sel_hi:[1,0]
	v_pk_mul_f32 v[32:33], v[32:33], v[200:201] op_sel_hi:[1,0]
	v_pk_mul_f32 v[30:31], v[30:31], v[200:201] op_sel_hi:[1,0]
	v_pk_mul_f32 v[28:29], v[28:29], v[200:201] op_sel_hi:[1,0]
	v_pk_mul_f32 v[26:27], v[26:27], v[200:201] op_sel_hi:[1,0]
	v_pk_mul_f32 v[24:25], v[24:25], v[200:201] op_sel_hi:[1,0]
	v_pk_mul_f32 v[22:23], v[22:23], v[200:201] op_sel_hi:[1,0]
	v_pk_mul_f32 v[20:21], v[20:21], v[200:201] op_sel_hi:[1,0]
	v_pk_mul_f32 v[18:19], v[18:19], v[200:201] op_sel_hi:[1,0]
	v_pk_mul_f32 v[16:17], v[16:17], v[200:201] op_sel_hi:[1,0]
	v_pk_mul_f32 v[14:15], v[14:15], v[200:201] op_sel_hi:[1,0]
	v_pk_mul_f32 v[12:13], v[12:13], v[200:201] op_sel_hi:[1,0]
	v_pk_mul_f32 v[10:11], v[10:11], v[200:201] op_sel_hi:[1,0]
	v_pk_mul_f32 v[8:9], v[8:9], v[200:201] op_sel_hi:[1,0]
	v_pk_mul_f32 v[6:7], v[6:7], v[200:201] op_sel_hi:[1,0]
	v_pk_mul_f32 v[4:5], v[4:5], v[200:201] op_sel_hi:[1,0]
	v_pk_mul_f32 v[2:3], v[2:3], v[200:201] op_sel_hi:[1,0]
